# attention: the two waves of a head split K/V fragment loads (K by one, V by the other) and exchange halves through LDS with one barrier per 32-key block
# baseline (speedup 1.0000x reference)
.LBB0_211:
	s_or_b64 exec, exec, s[0:1]
	s_abs_i32 s1, s2
	v_readlane_b32 s3, v255, 12
	s_mul_hi_u32 s3, s1, s3
	v_readlane_b32 s6, v255, 11
	s_mul_i32 s4, s3, s6
	s_sub_i32 s1, s1, s4
	s_ashr_i32 s0, s2, 31
	s_add_i32 s4, s3, 1
	s_sub_i32 s5, s1, s6
	s_cmp_ge_u32 s1, s6
	s_cselect_b32 s3, s4, s3
	s_cselect_b32 s1, s5, s1
	s_add_i32 s4, s3, 1
	s_cmp_ge_u32 s1, s6
	s_cselect_b32 s1, s4, s3
	s_xor_b32 s1, s1, s0
	s_sub_i32 s7, s1, s0
	s_mul_i32 s0, s7, s6
	v_mov_b32_e32 v0, v203
	s_sub_i32 s24, s2, s0
	s_and_b32 s19, s24, 1
	v_readfirstlane_b32 s4, v0
	s_ashr_i32 s18, s4, 6
	s_and_b32 s0, s18, 3
	s_lshl_b32 s1, s19, 2
	v_and_b32_e32 v1, 63, v0
	s_or_b32 s5, s0, s1
	s_mul_i32 s0, s18, 0x1200
	s_ashr_i32 s25, s4, 8
	s_add_i32 s6, s0, 0
	v_and_b32_e32 v165, 15, v0
	v_lshlrev_b32_e32 v0, 4, v1
	v_lshrrev_b32_e32 v152, 3, v1
	s_mov_b64 s[0:1], -1
	s_cmpk_gt_i32 s24, 0x7f
	v_lshrrev_b32_e32 v166, 4, v1
	v_and_b32_e32 v130, 48, v1
	v_and_b32_e32 v8, 0x70, v0
	v_mul_u32_u24_e32 v151, 0x90, v152
	v_mul_u32_u24_e32 v150, 0x90, v165
	v_lshlrev_b32_e32 v132, 6, v165
	s_cbranch_scc0 .LBB0_229
	s_and_b32 s0, s24, 0x7fffffe
	s_add_i32 s0, s0, s25
	s_lshl_b32 s0, s0, 5
	s_lshl_b32 s1, s7, 8
	s_add_i32 s2, s0, s1
	s_addk_i32 s2, 0x7000
	v_or_b32_e32 v6, s2, v152
	v_mov_b64_e32 v[4:5], s[70:71]
	v_mad_i64_i32 v[0:1], s[0:1], v6, s77, v[4:5]
	s_lshl_b32 s26, s5, 7
	v_lshl_add_u64 v[0:1], v[0:1], 0, s[26:27]
	v_lshl_add_u64 v[0:1], v[0:1], 0, v[8:9]
	global_load_dwordx4 v[0:3], v[0:1], off offset:2048
	v_add3_u32 v7, s6, v8, v151
	s_lshl_b32 s3, s5, 6
	v_mov_b32_e32 v133, v9
	v_mov_b32_e32 v131, v9
	v_mov_b32_e32 v56, v9
	v_mov_b32_e32 v57, v9
	v_mov_b32_e32 v195, v194
	v_mov_b32_e32 v54, v9
	v_mov_b32_e32 v55, v9
	v_mov_b64_e32 v[72:73], v[56:57]
	v_mov_b64_e32 v[76:77], v[56:57]
	v_mov_b64_e32 v[80:81], v[56:57]
	v_mov_b64_e32 v[100:101], v[56:57]
	v_mov_b64_e32 v[104:105], v[56:57]
	v_mov_b64_e32 v[108:109], v[56:57]
	v_mov_b64_e32 v[112:113], v[56:57]
	v_mov_b32_e32 v140, 0
	v_mov_b64_e32 v[70:71], v[54:55]
	v_mov_b64_e32 v[74:75], v[54:55]
	v_mov_b64_e32 v[78:79], v[54:55]
	v_mov_b64_e32 v[98:99], v[54:55]
	v_mov_b64_e32 v[102:103], v[54:55]
	v_mov_b64_e32 v[106:107], v[54:55]
	v_mov_b64_e32 v[110:111], v[54:55]
	v_mov_b64_e32 v[142:143], v[194:195]
	v_mov_b32_e32 v82, 0
	s_waitcnt vmcnt(0)
	ds_write_b128 v7, v[0:3] offset:34816
	v_or_b32_e32 v0, 8, v6
	v_mad_i64_i32 v[0:1], s[0:1], v0, s77, v[4:5]
	v_lshl_add_u64 v[0:1], v[0:1], 0, s[26:27]
	v_lshl_add_u64 v[0:1], v[0:1], 0, v[8:9]
	global_load_dwordx4 v[0:3], v[0:1], off offset:2048
	s_waitcnt vmcnt(0)
	ds_write_b128 v7, v[0:3] offset:35968
	v_or_b32_e32 v0, 16, v6
	v_mad_i64_i32 v[0:1], s[0:1], v0, s77, v[4:5]
	v_lshl_add_u64 v[0:1], v[0:1], 0, s[26:27]
	v_lshl_add_u64 v[0:1], v[0:1], 0, v[8:9]
	global_load_dwordx4 v[0:3], v[0:1], off offset:2048
	s_waitcnt vmcnt(0)
	ds_write_b128 v7, v[0:3] offset:37120
	v_or_b32_e32 v0, 24, v6
	v_mad_i64_i32 v[0:1], s[0:1], v0, s77, v[4:5]
	v_lshl_add_u64 v[0:1], v[0:1], 0, s[26:27]
	v_lshl_add_u64 v[0:1], v[0:1], 0, v[8:9]
	global_load_dwordx4 v[0:3], v[0:1], off offset:2048
	s_lshl_b32 s0, s7, 3
	s_or_b32 s0, s5, s0
	s_ashr_i32 s1, s0, 31
	s_lshl_b64 s[0:1], s[0:1], 15
	s_add_u32 s28, s69, s0
	s_addc_u32 s29, s72, s1
	s_add_u32 s0, s73, s0
	s_addc_u32 s1, s74, s1
	v_add3_u32 v4, s6, v150, v130
	v_add_u32_e32 v153, 0x8800, v4
	s_waitcnt vmcnt(0)
	ds_write_b128 v7, v[0:3] offset:38272
	v_lshl_add_u64 v[2:3], s[0:1], 0, v[132:133]
	v_lshl_add_u64 v[0:1], s[28:29], 0, v[132:133]
	v_lshl_add_u64 v[136:137], v[2:3], 0, v[130:131]
	v_lshl_add_u64 v[138:139], v[0:1], 0, v[130:131]
	v_bfe_i32 v241, v203, 8, 1
	v_and_b32_e32 v240, 0xc0, v203
	v_lshlrev_b32_e32 v240, 8, v240
	v_readfirstlane_b32 s98, v241
	v_lshl_add_u32 v240, v220, 4, v240
	v_add_u32_e32 v240, 0x11800, v240
	s_mov_b32 s99, s98
	s_mov_b64 vcc, s[98:99]
	s_cbranch_vccnz .Lkv_k_c0
	global_load_dwordx4 v[62:65], v[136:137], off
	global_load_dwordx4 v[58:61], v[136:137], off offset:1024
	global_load_dwordx4 v[66:69], v[136:137], off offset:2048
	global_load_dwordx4 v[50:53], v[136:137], off offset:3072
.Lkv_k_c0:
	s_mov_b64 vcc, s[98:99]
	s_cbranch_vccz .Lkv_v_c0
	global_load_dwordx4 v[42:45], v[138:139], off
	global_load_dwordx4 v[46:49], v[138:139], off offset:1024
	global_load_dwordx4 v[38:41], v[138:139], off offset:2048
	global_load_dwordx4 v[34:37], v[138:139], off offset:3072
.Lkv_v_c0:
	v_add_u32_e32 v131, 0x9100, v4
	s_movk_i32 s28, 0x1000
	v_mov_b64_e32 v[144:145], v[138:139]
	v_mov_b64_e32 v[146:147], v[136:137]
	s_branch .LBB0_216

.LBB0_216:
	v_mov_b64_e32 v[30:31], v[110:111]
	v_mov_b64_e32 v[26:27], v[106:107]
	v_mov_b64_e32 v[4:5], v[102:103]
	v_mov_b64_e32 v[0:1], v[98:99]
	v_mov_b64_e32 v[22:23], v[78:79]
	v_mov_b64_e32 v[18:19], v[74:75]
	v_mov_b64_e32 v[14:15], v[70:71]
	v_mov_b64_e32 v[10:11], v[54:55]
	v_mov_b32_e32 v134, v140
	v_mov_b64_e32 v[32:33], v[112:113]
	v_mov_b64_e32 v[28:29], v[108:109]
	v_mov_b64_e32 v[6:7], v[104:105]
	v_mov_b64_e32 v[2:3], v[100:101]
	v_mov_b64_e32 v[24:25], v[80:81]
	v_mov_b64_e32 v[20:21], v[76:77]
	v_mov_b64_e32 v[16:17], v[72:73]
	v_mov_b64_e32 v[12:13], v[56:57]
	v_mov_b32_e32 v135, v82
	s_cmpk_eq_i32 s28, 0x5000
	s_mov_b64 s[0:1], -1
	s_cbranch_scc1 .LBB0_215
	v_add_co_u32_e32 v54, vcc, 0x1000, v146
	v_mov_b32_e32 v102, v153
	s_nop 0
	v_addc_co_u32_e32 v55, vcc, 0, v147, vcc
	s_mov_b64 vcc, s[98:99]
	s_cbranch_vccnz .Lkv_k_c1
	global_load_dwordx4 v[94:97], v[54:55], off
	global_load_dwordx4 v[86:89], v[54:55], off offset:1024
	global_load_dwordx4 v[90:93], v[54:55], off offset:2048
	global_load_dwordx4 v[82:85], v[54:55], off offset:3072
.Lkv_k_c1:
	v_add_co_u32_e32 v54, vcc, 0x1000, v144
	s_nop 1
	v_addc_co_u32_e32 v55, vcc, 0, v145, vcc
	s_mov_b64 vcc, s[98:99]
	s_cbranch_vccz .Lkv_v_c1
	global_load_dwordx4 v[78:81], v[54:55], off
	global_load_dwordx4 v[74:77], v[54:55], off offset:1024
	global_load_dwordx4 v[70:73], v[54:55], off offset:2048
	global_load_dwordx4 v[54:57], v[54:55], off offset:3072
.Lkv_v_c1:
	s_waitcnt vmcnt(4)
	s_mov_b64 vcc, s[98:99]
	s_cbranch_vccnz .Lkv_wv_c1
	ds_write_b128 v240, v[62:65] offset:0
	ds_write_b128 v240, v[58:61] offset:1024
	ds_write_b128 v240, v[66:69] offset:2048
	ds_write_b128 v240, v[50:53] offset:3072
	s_branch .Lkv_wd_c1
.Lkv_wv_c1:
	ds_write_b128 v240, v[42:45] offset:4096
	ds_write_b128 v240, v[46:49] offset:5120
	ds_write_b128 v240, v[38:41] offset:6144
	ds_write_b128 v240, v[34:37] offset:7168
.Lkv_wd_c1:
	s_waitcnt lgkmcnt(0)
	s_barrier
	s_cbranch_vccnz .Lkv_rk_c1
	ds_read_b128 v[42:45], v240 offset:4096
	ds_read_b128 v[46:49], v240 offset:5120
	ds_read_b128 v[38:41], v240 offset:6144
	ds_read_b128 v[34:37], v240 offset:7168
	s_branch .Lkv_rd_c1
.Lkv_rk_c1:
	ds_read_b128 v[62:65], v240 offset:0
	ds_read_b128 v[58:61], v240 offset:1024
	ds_read_b128 v[66:69], v240 offset:2048
	ds_read_b128 v[50:53], v240 offset:3072
.Lkv_rd_c1:
	s_waitcnt lgkmcnt(0)
	ds_read_b128 v[98:101], v102
	ds_read_b128 v[102:105], v102 offset:64
	s_waitcnt vmcnt(15) lgkmcnt(1)
	v_mfma_f32_16x16x32_bf16 v[106:109], v[62:65], v[98:101], 0
	s_waitcnt vmcnt(13)
	v_mfma_f32_16x16x32_bf16 v[98:101], v[66:69], v[98:101], 0
	s_waitcnt vmcnt(12) lgkmcnt(0)
	v_mfma_f32_16x16x32_bf16 v[98:101], v[50:53], v[102:105], v[98:101]
	v_mfma_f32_16x16x32_bf16 v[112:115], v[58:61], v[102:105], v[106:109]
	s_nop 6
	v_mul_f32_e32 v109, 0x3e38aa3b, v100
	v_mul_f32_e32 v108, 0x3e38aa3b, v101
	v_mul_f32_e32 v123, 0x3e38aa3b, v112
	v_mul_f32_e32 v111, 0x3e38aa3b, v98
	v_mul_f32_e32 v122, 0x3e38aa3b, v113
	v_mul_f32_e32 v110, 0x3e38aa3b, v99
	v_mul_f32_e32 v113, 0x3e38aa3b, v114
	v_mul_f32_e32 v112, 0x3e38aa3b, v115
	v_max_f32_e32 v100, v109, v108
	v_max_f32_e32 v98, v123, v122
	v_max_f32_e32 v99, v113, v112
	v_max3_f32 v100, v111, v110, v100
	v_max3_f32 v98, v98, v99, v100
	v_and_b32_e32 v100, 64, v220
	v_xor_b32_e32 v99, 16, v220
	v_add_u32_e32 v100, 64, v100
	v_cmp_lt_i32_e32 vcc, v99, v100
	s_nop 1
	v_cndmask_b32_e32 v99, v220, v99, vcc
	v_lshlrev_b32_e32 v154, 2, v99
	ds_bpermute_b32 v99, v154, v98
	s_waitcnt lgkmcnt(0)
	v_max_f32_e32 v99, v99, v99
	v_max_f32_e32 v98, v98, v99
	v_xor_b32_e32 v99, 32, v220
	v_cmp_lt_i32_e32 vcc, v99, v100
	s_nop 1
	v_cndmask_b32_e32 v99, v220, v99, vcc
	v_lshlrev_b32_e32 v133, 2, v99
	ds_bpermute_b32 v99, v133, v98
	s_waitcnt lgkmcnt(0)
	v_max_f32_e32 v99, v99, v99
	v_max_f32_e32 v98, v98, v99
	v_cmp_gt_f32_e32 vcc, v98, v142
	s_cbranch_vccz .LBB0_219
	v_max_f32_e32 v98, v98, v98
	v_max_f32_e32 v99, v142, v142
	v_max_f32_e32 v106, v99, v98
	v_sub_f32_e32 v98, v142, v106
	v_exp_f32_e32 v118, v98
	v_mov_b32_e32 v107, v143
	v_mov_b32_e32 v141, v135
	v_mov_b64_e32 v[142:143], v[106:107]
	v_mul_f32_e32 v140, v134, v118
	v_pk_mul_f32 v[100:101], v[32:33], v[118:119] op_sel_hi:[1,0]
	v_pk_mul_f32 v[98:99], v[30:31], v[118:119] op_sel_hi:[1,0]
	v_pk_mul_f32 v[104:105], v[28:29], v[118:119] op_sel_hi:[1,0]
	v_pk_mul_f32 v[102:103], v[26:27], v[118:119] op_sel_hi:[1,0]
	v_pk_mul_f32 v[116:117], v[6:7], v[118:119] op_sel_hi:[1,0]
	v_pk_mul_f32 v[114:115], v[4:5], v[118:119] op_sel_hi:[1,0]
	v_pk_mul_f32 v[120:121], v[2:3], v[118:119] op_sel_hi:[1,0]
	v_pk_mul_f32 v[118:119], v[0:1], v[118:119] op_sel_hi:[1,0]
	s_branch .LBB0_220

.LBB0_223:
	v_sub_f32_e32 v121, v121, v122
	v_exp_f32_e32 v121, v121
	v_sub_f32_e32 v120, v120, v122
	v_exp_f32_e32 v120, v120
	v_sub_f32_e32 v119, v119, v122
	v_exp_f32_e32 v119, v119
	v_sub_f32_e32 v118, v118, v122
	v_exp_f32_e32 v118, v118
	v_sub_f32_e32 v117, v117, v122
	v_add_f32_e32 v123, 0, v121
	v_exp_f32_e32 v117, v117
	v_sub_f32_e32 v116, v116, v122
	v_add_f32_e32 v123, v120, v123
	v_exp_f32_e32 v116, v116
	v_sub_f32_e32 v115, v115, v122
	v_add_f32_e32 v123, v119, v123
	v_exp_f32_e32 v124, v115
	v_sub_f32_e32 v114, v114, v122
	v_add_f32_e32 v123, v118, v123
	v_exp_f32_e32 v122, v114
	v_add_f32_e32 v123, v117, v123
	s_cmpk_lg_i32 s28, 0x4000
	v_add_f32_e32 v123, v116, v123
	s_cselect_b32 s26, s28, 0x3000
	v_add_f32_e32 v115, v124, v123
	s_lshl_b64 s[0:1], s[26:27], 1
	v_add_f32_e32 v114, v122, v115
	v_lshl_add_u64 v[146:147], v[136:137], 0, s[0:1]
	v_add_f32_e32 v141, v141, v114
	v_cvt_pk_bf16_f32 v114, v121, v120
	v_cvt_pk_bf16_f32 v115, v119, v118
	v_cvt_pk_bf16_f32 v116, v117, v116
	v_cvt_pk_bf16_f32 v117, v124, v122
	v_lshl_add_u64 v[144:145], v[138:139], 0, s[0:1]
	v_mov_b32_e32 v148, v153
	v_mfma_f32_16x16x32_bf16 v[126:129], v[42:45], v[114:117], v[50:53]
	v_mfma_f32_16x16x32_bf16 v[122:125], v[46:49], v[114:117], v[66:69]
	v_mfma_f32_16x16x32_bf16 v[118:121], v[38:41], v[114:117], v[62:65]
	v_mfma_f32_16x16x32_bf16 v[114:117], v[34:37], v[114:117], v[58:61]
	s_nop 1
	s_mov_b64 vcc, s[98:99]
	s_cbranch_vccnz .Lkv_k_c2
	global_load_dwordx4 v[62:65], v[146:147], off
	global_load_dwordx4 v[58:61], v[146:147], off offset:1024
	global_load_dwordx4 v[66:69], v[146:147], off offset:2048
	global_load_dwordx4 v[50:53], v[146:147], off offset:3072
.Lkv_k_c2:
	s_mov_b64 vcc, s[98:99]
	s_cbranch_vccz .Lkv_v_c2
	global_load_dwordx4 v[42:45], v[144:145], off
	global_load_dwordx4 v[46:49], v[144:145], off offset:1024
	global_load_dwordx4 v[38:41], v[144:145], off offset:2048
	global_load_dwordx4 v[34:37], v[144:145], off offset:3072
.Lkv_v_c2:
	s_waitcnt vmcnt(4)
	s_mov_b64 vcc, s[98:99]
	s_cbranch_vccnz .Lkv_wv_c2
	ds_write_b128 v240, v[94:97] offset:8192
	ds_write_b128 v240, v[86:89] offset:9216
	ds_write_b128 v240, v[90:93] offset:10240
	ds_write_b128 v240, v[82:85] offset:11264
	s_branch .Lkv_wd_c2
.Lkv_wv_c2:
	ds_write_b128 v240, v[78:81] offset:12288
	ds_write_b128 v240, v[74:77] offset:13312
	ds_write_b128 v240, v[70:73] offset:14336
	ds_write_b128 v240, v[54:57] offset:15360
.Lkv_wd_c2:
	s_waitcnt lgkmcnt(0)
	s_barrier
	s_cbranch_vccnz .Lkv_rk_c2
	ds_read_b128 v[78:81], v240 offset:12288
	ds_read_b128 v[74:77], v240 offset:13312
	ds_read_b128 v[70:73], v240 offset:14336
	ds_read_b128 v[54:57], v240 offset:15360
	s_branch .Lkv_rd_c2
.Lkv_rk_c2:
	ds_read_b128 v[94:97], v240 offset:8192
	ds_read_b128 v[86:89], v240 offset:9216
	ds_read_b128 v[90:93], v240 offset:10240
	ds_read_b128 v[82:85], v240 offset:11264
.Lkv_rd_c2:
	s_waitcnt lgkmcnt(0)
	ds_read_b128 v[156:159], v148
	ds_read_b128 v[160:163], v148 offset:64
	s_waitcnt vmcnt(15) lgkmcnt(1)
	v_mfma_f32_16x16x32_bf16 v[168:171], v[94:97], v[156:159], 0
	s_waitcnt vmcnt(13)
	v_mfma_f32_16x16x32_bf16 v[156:159], v[90:93], v[156:159], 0
	s_waitcnt vmcnt(12) lgkmcnt(0)
	v_mfma_f32_16x16x32_bf16 v[172:175], v[82:85], v[160:163], v[156:159]
	v_mfma_f32_16x16x32_bf16 v[168:171], v[86:89], v[160:163], v[168:171]
	s_nop 6
	v_mul_f32_e32 v156, 0x3e38aa3b, v174
	v_mul_f32_e32 v155, 0x3e38aa3b, v175
	v_mul_f32_e32 v162, 0x3e38aa3b, v168
	v_mul_f32_e32 v158, 0x3e38aa3b, v172
	v_mul_f32_e32 v161, 0x3e38aa3b, v169
	v_mul_f32_e32 v157, 0x3e38aa3b, v173
	v_mul_f32_e32 v160, 0x3e38aa3b, v170
	v_mul_f32_e32 v159, 0x3e38aa3b, v171
	v_max_f32_e32 v163, v156, v155
	v_max_f32_e32 v148, v162, v161
	v_max_f32_e32 v149, v160, v159
	v_max3_f32 v163, v158, v157, v163
	v_max3_f32 v148, v148, v149, v163
	ds_bpermute_b32 v149, v154, v148
	s_waitcnt lgkmcnt(0)
	v_max_f32_e32 v149, v149, v149
	v_max_f32_e32 v148, v148, v149
	ds_bpermute_b32 v149, v133, v148
	s_waitcnt lgkmcnt(0)
	v_max_f32_e32 v149, v149, v149
	v_max_f32_e32 v148, v148, v149
	v_cmp_gt_f32_e32 vcc, v148, v142
	s_cbranch_vccz .LBB0_225
	v_max_f32_e32 v148, v148, v148
	v_max_f32_e32 v149, v142, v142
	v_max_f32_e32 v148, v149, v148
	v_sub_f32_e32 v142, v142, v148
	v_exp_f32_e32 v142, v142
	v_mov_b32_e32 v149, v143
	v_mul_f32_e32 v140, v140, v142
	v_pk_mul_f32 v[112:113], v[112:113], v[142:143] op_sel_hi:[1,0]
	v_pk_mul_f32 v[110:111], v[110:111], v[142:143] op_sel_hi:[1,0]
	v_pk_mul_f32 v[108:109], v[108:109], v[142:143] op_sel_hi:[1,0]
	v_pk_mul_f32 v[106:107], v[106:107], v[142:143] op_sel_hi:[1,0]
	v_pk_mul_f32 v[104:105], v[104:105], v[142:143] op_sel_hi:[1,0]
	v_pk_mul_f32 v[102:103], v[102:103], v[142:143] op_sel_hi:[1,0]
	v_pk_mul_f32 v[100:101], v[100:101], v[142:143] op_sel_hi:[1,0]
	v_pk_mul_f32 v[98:99], v[98:99], v[142:143] op_sel_hi:[1,0]
	v_mov_b64_e32 v[142:143], v[148:149]
	s_branch .LBB0_226

.LBB0_229:
	s_and_b64 vcc, exec, s[0:1]
	s_cbranch_vccz .LBB0_202
	s_ashr_i32 s2, s24, 1
	s_lshl_b32 s0, s7, 12
	s_lshl_b32 s1, s2, 6
	s_add_i32 s0, s1, s0
	s_lshl_b32 s3, s25, 5
	v_writelane_b32 v255, s34, 29
	s_add_i32 s0, s0, s3
	v_or_b32_e32 v14, s0, v152
	v_writelane_b32 v255, s35, 30
	v_mov_b64_e32 v[10:11], s[70:71]
	v_writelane_b32 v255, s0, 31
	s_waitcnt lgkmcnt(0)
	v_mad_i64_i32 v[0:1], s[0:1], v14, s77, v[10:11]
	v_or_b32_e32 v2, 8, v14
	v_or_b32_e32 v12, 16, v14
	v_or_b32_e32 v14, 24, v14
	s_lshl_b32 s26, s5, 7
	v_mad_i64_i32 v[2:3], s[0:1], v2, s77, v[10:11]
	v_mad_i64_i32 v[12:13], s[0:1], v12, s77, v[10:11]
	v_mad_i64_i32 v[10:11], s[0:1], v14, s77, v[10:11]
	v_lshl_add_u64 v[0:1], v[0:1], 0, s[26:27]
	v_lshl_add_u64 v[2:3], v[2:3], 0, s[26:27]
	v_lshl_add_u64 v[12:13], v[12:13], 0, s[26:27]
	v_lshl_add_u64 v[10:11], v[10:11], 0, s[26:27]
	v_lshl_add_u64 v[0:1], v[0:1], 0, v[8:9]
	v_lshl_add_u64 v[4:5], v[2:3], 0, v[8:9]
	v_lshl_add_u64 v[12:13], v[12:13], 0, v[8:9]
	v_lshl_add_u64 v[14:15], v[10:11], 0, v[8:9]
	global_load_dwordx4 v[0:3], v[0:1], off offset:2048
	s_nop 0
	global_load_dwordx4 v[4:7], v[4:5], off offset:2048
	s_nop 0
	global_load_dwordx4 v[10:13], v[12:13], off offset:2048
	s_nop 0
	global_load_dwordx4 v[14:17], v[14:15], off offset:2048
	s_lshl_b32 s0, s18, 12
	s_lshl_b32 s18, s5, 6
	s_lshl_b32 s7, s7, 3
	s_lshl_b32 s1, s19, 11
	v_writelane_b32 v255, s18, 32
	v_add3_u32 v8, s6, v8, v151
	v_add3_u32 v21, s6, v150, v130
	s_add_i32 s6, s0, 0
	s_max_i32 s18, s2, 4
	s_or_b32 s0, s5, s7
	v_or_b32_e32 v22, s3, v165
	s_add_i32 s3, s6, s1
	s_add_i32 s18, s18, -4
	s_ashr_i32 s1, s0, 31
	v_max_i32_e32 v18, 8, v22
	v_or_b32_e32 v23, 16, v22
	s_min_u32 s26, s18, 56
	s_lshl_b64 s[6:7], s[0:1], 15
	v_add_u32_e32 v18, -8, v18
	v_max_i32_e32 v19, 8, v23
	s_add_u32 s18, s69, s6
	v_mov_b32_e32 v133, v9
	v_min_u32_e32 v24, 48, v18
	v_add_u32_e32 v18, -8, v19
	s_addc_u32 s19, s72, s7
	s_lshl_b32 s5, s26, 13
	s_lshl_b64 s[0:1], s[0:1], 19
	v_min_u32_e32 v25, 48, v18
	v_lshl_add_u64 v[18:19], s[18:19], 0, v[132:133]
	s_add_u32 s18, s75, s0
	s_addc_u32 s19, s76, s1
	s_add_u32 s18, s18, s5
	v_mov_b32_e32 v131, v9
	s_addc_u32 s19, s19, 0
	v_lshl_add_u64 v[140:141], v[18:19], 0, v[130:131]
	v_lshl_add_u64 v[18:19], s[18:19], 0, v[132:133]
	v_readlane_b32 s18, v251, 53
	v_readlane_b32 s19, v251, 54
	s_add_u32 s0, s18, s0
	s_addc_u32 s1, s19, s1
	s_add_u32 s0, s0, s5
	s_addc_u32 s1, s1, 0
	v_lshl_add_u64 v[142:143], v[18:19], 0, v[130:131]
	v_lshl_add_u64 v[18:19], s[0:1], 0, v[132:133]
	s_add_u32 s0, s73, s6
	s_addc_u32 s1, s74, s7
	v_lshl_add_u64 v[144:145], v[18:19], 0, v[130:131]
	v_lshl_add_u64 v[18:19], s[0:1], 0, v[132:133]
	v_lshl_add_u64 v[146:147], v[18:19], 0, v[130:131]
	v_lshlrev_b32_e32 v20, 3, v166
	s_cmpk_lt_u32 s4, 0x100
	s_movk_i32 s0, 0xffe0
	s_cselect_b64 s[18:19], -1, 0
	s_cmpk_gt_u32 s4, 0xff
	s_cselect_b64 s[24:25], -1, 0
	s_waitcnt vmcnt(3)
	ds_write_b128 v8, v[0:3] offset:34816
	s_waitcnt vmcnt(2)
	ds_write_b128 v8, v[4:7] offset:35968
	s_waitcnt vmcnt(1)
	ds_write_b128 v8, v[10:13] offset:37120
	s_waitcnt vmcnt(0)
	ds_write_b128 v8, v[14:17] offset:38272
	v_bfe_i32 v241, v203, 8, 1
	v_and_b32_e32 v240, 0xc0, v203
	v_lshlrev_b32_e32 v240, 8, v240
	v_readfirstlane_b32 s98, v241
	v_lshl_add_u32 v240, v220, 4, v240
	v_add_u32_e32 v240, 0x11800, v240
	s_mov_b32 s99, s98
	s_mov_b64 vcc, s[98:99]
	s_cbranch_vccnz .Lkv_k_w0
	global_load_dwordx4 v[82:85], v[146:147], off
	global_load_dwordx4 v[74:77], v[146:147], off offset:1024
	global_load_dwordx4 v[86:89], v[146:147], off offset:2048
	global_load_dwordx4 v[78:81], v[146:147], off offset:3072
.Lkv_k_w0:
	s_mov_b64 vcc, s[98:99]
	s_cbranch_vccz .Lkv_v_w0
	global_load_dwordx4 v[54:57], v[140:141], off
	global_load_dwordx4 v[50:53], v[140:141], off offset:1024
	global_load_dwordx4 v[46:49], v[140:141], off offset:2048
	global_load_dwordx4 v[42:45], v[140:141], off offset:3072
.Lkv_v_w0:
	v_sub_u32_e32 v0, v20, v24
	v_and_b32_e32 v17, -16, v0
	v_cmp_eq_u32_e64 s[4:5], s0, v17
	v_add_u32_e32 v17, 33, v0
	v_cmp_gt_u32_e64 s[44:45], 16, v17
	v_add_u32_e32 v17, 35, v0
	v_cmp_gt_u32_e64 s[48:49], 16, v17
	v_add_u32_e32 v17, 37, v0
	v_sub_u32_e32 v8, v20, v25
	v_add_u32_e32 v18, 34, v0
	v_cmp_gt_u32_e64 s[52:53], 16, v17
	v_add_u32_e32 v17, 39, v0
	v_cmp_gt_u32_e64 s[42:43], 16, v18
	v_add_u32_e32 v18, 36, v0
	v_cmp_gt_u32_e64 s[54:55], 16, v17
	v_and_b32_e32 v17, -16, v8
	v_cmp_gt_u32_e64 s[46:47], 16, v18
	v_add_u32_e32 v18, 38, v0
	v_cmp_eq_u32_e64 s[56:57], s0, v17
	v_add_u32_e32 v17, 33, v8
	v_cmp_gt_u32_e64 s[50:51], 16, v18
	v_add_u32_e32 v18, 34, v8
	v_cmp_gt_u32_e64 s[60:61], 16, v17
	v_add_u32_e32 v17, 35, v8
	v_add_u32_e32 v10, 1, v8
	v_add_u32_e32 v11, 2, v8
	v_writelane_b32 v255, s4, 33
	v_cmp_gt_u32_e64 s[58:59], 16, v18
	v_add_u32_e32 v18, 36, v8
	v_cmp_gt_u32_e64 s[64:65], 16, v17
	v_add_u32_e32 v17, 37, v8
	v_add_u32_e32 v1, 1, v0
	v_add_u32_e32 v2, 2, v0
	v_add_u32_e32 v3, 3, v0
	v_add_u32_e32 v4, 4, v0
	v_add_u32_e32 v5, 5, v0
	v_add_u32_e32 v6, 6, v0
	v_add_u32_e32 v7, 7, v0
	v_add_u32_e32 v12, 3, v8
	v_add_u32_e32 v13, 4, v8
	v_add_u32_e32 v14, 5, v8
	v_add_u32_e32 v15, 6, v8
	v_add_u32_e32 v16, 7, v8
	v_writelane_b32 v255, s5, 34
	v_cmp_gt_u32_e64 s[62:63], 16, v18
	v_add_u32_e32 v18, 38, v8
	v_cmp_gt_u32_e64 s[68:69], 16, v17
	v_add_u32_e32 v17, 39, v8
	v_cmp_gt_u32_e64 s[88:89], 16, v8
	v_cmp_gt_u32_e64 s[4:5], 16, v11
	v_cmp_gt_u32_e64 s[6:7], 16, v10
	v_mov_b32_e32 v8, v9
	v_mov_b32_e32 v10, v9
	v_mov_b32_e32 v11, v9
	v_cmp_gt_u32_e64 s[72:73], 16, v0
	v_cmp_gt_u32_e64 s[74:75], 16, v7
	v_cmp_gt_u32_e64 s[76:77], 16, v6
	v_cmp_gt_u32_e64 s[78:79], 16, v5
	v_cmp_gt_u32_e64 s[80:81], 16, v4
	v_cmp_gt_u32_e64 s[82:83], 16, v3
	v_cmp_gt_u32_e64 s[84:85], 16, v2
	v_cmp_gt_u32_e64 s[86:87], 16, v1
	s_lshl_b32 s26, s26, 5
	s_lshl_b32 s2, s2, 5
	v_mov_b32_e32 v195, v194
	v_mov_b64_e32 v[60:61], v[10:11]
	v_mov_b64_e32 v[64:65], v[10:11]
	v_mov_b64_e32 v[4:5], v[8:9]
	v_mov_b64_e32 v[0:1], v[8:9]
	v_mov_b64_e32 v[104:105], v[10:11]
	v_mov_b64_e32 v[100:101], v[10:11]
	v_mov_b64_e32 v[96:97], v[10:11]
	v_mov_b64_e32 v[92:93], v[10:11]
	v_add_u32_e32 v167, 0x8800, v21
	v_add_u32_e32 v168, 0x9100, v21
	v_cmp_gt_u32_e64 s[66:67], 16, v18
	v_cmp_gt_u32_e64 s[70:71], 16, v17
	v_cmp_gt_u32_e64 s[90:91], 16, v16
	v_cmp_gt_u32_e64 s[92:93], 16, v15
	v_cmp_gt_u32_e64 s[94:95], 16, v14
	v_cmp_gt_u32_e64 s[96:97], 16, v13
	v_cmp_gt_u32_e64 s[0:1], 16, v12
	v_sub_u32_e32 v169, v20, v22
	v_sub_u32_e32 v170, v20, v23
	s_sub_i32 s34, s26, s2
	s_mov_b32 s2, 0
	v_mov_b32_e32 v154, 0
	s_movk_i32 s35, 0x60
	v_mov_b64_e32 v[58:59], v[8:9]
	v_mov_b64_e32 v[62:63], v[8:9]
	v_mov_b64_e32 v[6:7], v[10:11]
	v_mov_b64_e32 v[2:3], v[10:11]
	v_mov_b64_e32 v[102:103], v[8:9]
	v_mov_b64_e32 v[98:99], v[8:9]
	v_mov_b64_e32 v[94:95], v[8:9]
	v_mov_b64_e32 v[90:91], v[8:9]
	v_mov_b64_e32 v[150:151], v[140:141]
	v_mov_b64_e32 v[148:149], v[146:147]
	v_mov_b64_e32 v[152:153], v[194:195]
	v_mov_b32_e32 v8, 0
	s_branch .LBB0_235

.LBB0_235:
	v_mov_b64_e32 v[38:39], v[90:91]
	v_mov_b64_e32 v[34:35], v[94:95]
	v_mov_b64_e32 v[30:31], v[98:99]
	v_mov_b64_e32 v[26:27], v[102:103]
	v_mov_b64_e32 v[24:25], v[2:3]
	v_mov_b64_e32 v[20:21], v[6:7]
	v_mov_b64_e32 v[14:15], v[62:63]
	v_mov_b64_e32 v[10:11], v[58:59]
	v_mov_b32_e32 v138, v154
	v_mov_b64_e32 v[40:41], v[92:93]
	v_mov_b64_e32 v[36:37], v[96:97]
	v_mov_b64_e32 v[32:33], v[100:101]
	v_mov_b64_e32 v[28:29], v[104:105]
	v_mov_b64_e32 v[22:23], v[0:1]
	v_mov_b64_e32 v[18:19], v[4:5]
	v_mov_b64_e32 v[16:17], v[64:65]
	v_mov_b64_e32 v[12:13], v[60:61]
	v_mov_b32_e32 v139, v8
	s_cmpk_eq_i32 s35, 0x1e0
	s_mov_b64 s[36:37], -1
	s_cbranch_scc1 .LBB0_234
	v_add_co_u32_e32 v0, vcc, 0x1000, v148
	s_add_i32 s40, s2, 1
	s_nop 0
	v_addc_co_u32_e32 v1, vcc, 0, v149, vcc
	s_mov_b64 vcc, s[98:99]
	s_cbranch_vccnz .Lkv_k_w1
	global_load_dwordx4 v[114:117], v[0:1], off
	global_load_dwordx4 v[110:113], v[0:1], off offset:1024
	global_load_dwordx4 v[118:121], v[0:1], off offset:2048
	global_load_dwordx4 v[106:109], v[0:1], off offset:3072
.Lkv_k_w1:
	v_add_co_u32_e32 v0, vcc, 0x1000, v150
	s_cmp_lg_u32 s2, 11
	s_nop 0
	v_addc_co_u32_e32 v1, vcc, 0, v151, vcc
	s_mov_b64 vcc, s[98:99]
	s_cbranch_vccz .Lkv_v_w1
	global_load_dwordx4 v[70:73], v[0:1], off
	global_load_dwordx4 v[66:69], v[0:1], off offset:1024
	global_load_dwordx4 v[62:65], v[0:1], off offset:2048
	global_load_dwordx4 v[58:61], v[0:1], off offset:3072
.Lkv_v_w1:
	s_waitcnt vmcnt(4)
	s_mov_b64 vcc, s[98:99]
	s_cbranch_vccnz .Lkv_wv_w1
	ds_write_b128 v240, v[82:85] offset:0
	ds_write_b128 v240, v[74:77] offset:1024
	ds_write_b128 v240, v[86:89] offset:2048
	ds_write_b128 v240, v[78:81] offset:3072
	s_branch .Lkv_wd_w1
.Lkv_wv_w1:
	ds_write_b128 v240, v[54:57] offset:4096
	ds_write_b128 v240, v[50:53] offset:5120
	ds_write_b128 v240, v[46:49] offset:6144
	ds_write_b128 v240, v[42:45] offset:7168
.Lkv_wd_w1:
	s_waitcnt lgkmcnt(0)
	s_barrier
	s_cbranch_vccnz .Lkv_rk_w1
	ds_read_b128 v[54:57], v240 offset:4096
	ds_read_b128 v[50:53], v240 offset:5120
	ds_read_b128 v[46:49], v240 offset:6144
	ds_read_b128 v[42:45], v240 offset:7168
	s_branch .Lkv_rd_w1
.Lkv_rk_w1:
	ds_read_b128 v[82:85], v240 offset:0
	ds_read_b128 v[74:77], v240 offset:1024
	ds_read_b128 v[86:89], v240 offset:2048
	ds_read_b128 v[78:81], v240 offset:3072
.Lkv_rd_w1:
	s_waitcnt lgkmcnt(0)
	s_cselect_b32 s41, s40, 11
	s_cmp_gt_u32 s41, 3
	s_cselect_b64 s[36:37], -1, 0
	s_mov_b64 s[38:39], -1
	s_and_b64 vcc, exec, s[36:37]
	s_cbranch_vccnz .LBB0_247
	s_andn2_b64 vcc, exec, s[38:39]
	s_cbranch_vccz .LBB0_248

.LBB0_262:
	s_nop 0
	s_mov_b64 vcc, s[98:99]
	s_cbranch_vccnz .Lkv_k_w2
	global_load_dwordx4 v[82:85], v[148:149], off
	global_load_dwordx4 v[74:77], v[148:149], off offset:1024
	global_load_dwordx4 v[86:89], v[148:149], off offset:2048
	global_load_dwordx4 v[78:81], v[148:149], off offset:3072
.Lkv_k_w2:
	s_mov_b64 vcc, s[98:99]
	s_cbranch_vccz .Lkv_v_w2
	global_load_dwordx4 v[54:57], v[150:151], off
	global_load_dwordx4 v[50:53], v[150:151], off offset:1024
	global_load_dwordx4 v[46:49], v[150:151], off offset:2048
	global_load_dwordx4 v[42:45], v[150:151], off offset:3072
.Lkv_v_w2:
	s_waitcnt vmcnt(4)
	s_mov_b64 vcc, s[98:99]
	s_cbranch_vccnz .Lkv_wv_w2
	ds_write_b128 v240, v[114:117] offset:8192
	ds_write_b128 v240, v[110:113] offset:9216
	ds_write_b128 v240, v[118:121] offset:10240
	ds_write_b128 v240, v[106:109] offset:11264
	s_branch .Lkv_wd_w2
.Lkv_wv_w2:
	ds_write_b128 v240, v[70:73] offset:12288
	ds_write_b128 v240, v[66:69] offset:13312
	ds_write_b128 v240, v[62:65] offset:14336
	ds_write_b128 v240, v[58:61] offset:15360
.Lkv_wd_w2:
	s_waitcnt lgkmcnt(0)
	s_barrier
	s_cbranch_vccnz .Lkv_rk_w2
	ds_read_b128 v[70:73], v240 offset:12288
	ds_read_b128 v[66:69], v240 offset:13312
	ds_read_b128 v[62:65], v240 offset:14336
	ds_read_b128 v[58:61], v240 offset:15360
	s_branch .Lkv_rd_w2
.Lkv_rk_w2:
	ds_read_b128 v[114:117], v240 offset:8192
	ds_read_b128 v[110:113], v240 offset:9216
	ds_read_b128 v[118:121], v240 offset:10240
	ds_read_b128 v[106:109], v240 offset:11264
.Lkv_rd_w2:
	s_waitcnt lgkmcnt(0)
	s_or_b64 s[28:29], s[38:39], s[24:25]
	s_mov_b64 s[38:39], -1
	s_and_b64 vcc, exec, s[28:29]
	s_cbranch_vccnz .LBB0_264
	s_mov_b64 s[38:39], 0

	.amdhsa_kernel _Z6mk_fwdILb1EEv4Args
		.amdhsa_group_segment_fixed_size 0
		.amdhsa_private_segment_fixed_size 0
		.amdhsa_kernarg_size 440
		.amdhsa_user_sgpr_count 2
		.amdhsa_user_sgpr_dispatch_ptr 0
		.amdhsa_user_sgpr_queue_ptr 0
		.amdhsa_user_sgpr_kernarg_segment_ptr 1
		.amdhsa_user_sgpr_dispatch_id 0
		.amdhsa_user_sgpr_kernarg_preload_length 0
		.amdhsa_user_sgpr_kernarg_preload_offset 0
		.amdhsa_user_sgpr_private_segment_size 0
		.amdhsa_uses_dynamic_stack 0
		.amdhsa_enable_private_segment 0
		.amdhsa_system_sgpr_workgroup_id_x 1
		.amdhsa_system_sgpr_workgroup_id_y 0
		.amdhsa_system_sgpr_workgroup_id_z 0
		.amdhsa_system_sgpr_workgroup_info 0
		.amdhsa_system_vgpr_workitem_id 2
		.amdhsa_next_free_vgpr 256
		.amdhsa_next_free_sgpr 100
		.amdhsa_accum_offset 256
		.amdhsa_reserve_vcc 1
		.amdhsa_float_round_mode_32 0
		.amdhsa_float_round_mode_16_64 0
		.amdhsa_float_denorm_mode_32 3
		.amdhsa_float_denorm_mode_16_64 3
		.amdhsa_dx10_clamp 1
		.amdhsa_ieee_mode 1
		.amdhsa_fp16_overflow 0
		.amdhsa_tg_split 0
		.amdhsa_exception_fp_ieee_invalid_op 0
		.amdhsa_exception_fp_denorm_src 0
		.amdhsa_exception_fp_ieee_div_zero 0
		.amdhsa_exception_fp_ieee_overflow 0
		.amdhsa_exception_fp_ieee_underflow 0
		.amdhsa_exception_fp_ieee_inexact 0
		.amdhsa_exception_int_div_zero 0
	.end_amdhsa_kernel

amdhsa.kernels:
  - .agpr_count:     0
    .args:
      - .offset:         0
        .size:           184
        .value_kind:     by_value
      - .offset:         184
        .size:           4
        .value_kind:     hidden_block_count_x
      - .offset:         188
        .size:           4
        .value_kind:     hidden_block_count_y
      - .offset:         192
        .size:           4
        .value_kind:     hidden_block_count_z
      - .offset:         196
        .size:           2
        .value_kind:     hidden_group_size_x
      - .offset:         198
        .size:           2
        .value_kind:     hidden_group_size_y
      - .offset:         200
        .size:           2
        .value_kind:     hidden_group_size_z
      - .offset:         202
        .size:           2
        .value_kind:     hidden_remainder_x
      - .offset:         204
        .size:           2
        .value_kind:     hidden_remainder_y
      - .offset:         206
        .size:           2
        .value_kind:     hidden_remainder_z
      - .offset:         224
        .size:           8
        .value_kind:     hidden_global_offset_x
      - .offset:         232
        .size:           8
        .value_kind:     hidden_global_offset_y
      - .offset:         240
        .size:           8
        .value_kind:     hidden_global_offset_z
      - .offset:         248
        .size:           2
        .value_kind:     hidden_grid_dims
      - .offset:         272
        .size:           8
        .value_kind:     hidden_multigrid_sync_arg
      - .offset:         304
        .size:           4
        .value_kind:     hidden_dynamic_lds_size
    .group_segment_fixed_size: 0
    .kernarg_segment_align: 8
    .kernarg_segment_size: 440
    .language:       OpenCL C
    .language_version:
      - 2
      - 0
    .max_flat_workgroup_size: 512
    .name:           _Z6mk_fwdILb1EEv4Args
    .private_segment_fixed_size: 0
    .sgpr_count:     106
    .sgpr_spill_count: 301
    .symbol:         _Z6mk_fwdILb1EEv4Args.kd
    .uniform_work_group_size: 1
    .uses_dynamic_stack: false
    .vgpr_count:     256
    .vgpr_spill_count: 0
    .wavefront_size: 64
  - .agpr_count:     0
    .args:
      - .offset:         0
        .size:           184
        .value_kind:     by_value
      - .offset:         184
        .size:           4
        .value_kind:     hidden_block_count_x
      - .offset:         188
        .size:           4
        .value_kind:     hidden_block_count_y
      - .offset:         192
        .size:           4
        .value_kind:     hidden_block_count_z
      - .offset:         196
        .size:           2
        .value_kind:     hidden_group_size_x
      - .offset:         198
        .size:           2
        .value_kind:     hidden_group_size_y
      - .offset:         200
        .size:           2
        .value_kind:     hidden_group_size_z
      - .offset:         202
        .size:           2
        .value_kind:     hidden_remainder_x
      - .offset:         204
        .size:           2
        .value_kind:     hidden_remainder_y
      - .offset:         206
        .size:           2
        .value_kind:     hidden_remainder_z
      - .offset:         224
        .size:           8
        .value_kind:     hidden_global_offset_x
      - .offset:         232
        .size:           8
        .value_kind:     hidden_global_offset_y
      - .offset:         240
        .size:           8
        .value_kind:     hidden_global_offset_z
      - .offset:         248
        .size:           2
        .value_kind:     hidden_grid_dims
      - .offset:         304
        .size:           4
        .value_kind:     hidden_dynamic_lds_size
    .group_segment_fixed_size: 0
    .kernarg_segment_align: 8
    .kernarg_segment_size: 440
    .language:       OpenCL C
    .language_version:
      - 2
      - 0
    .max_flat_workgroup_size: 512
    .name:           _Z6mk_fwdILb0EEv4Args
    .private_segment_fixed_size: 0
    .sgpr_count:     104
    .sgpr_spill_count: 216
    .symbol:         _Z6mk_fwdILb0EEv4Args.kd
    .uniform_work_group_size: 1
    .uses_dynamic_stack: false
    .vgpr_count:     256
    .vgpr_spill_count: 0
    .wavefront_size: 64
